# RET phase split into two sub-passes without grid barrier: half the workgroups do prompt units first and sample-state stream second, other half reversed; 16-deep sample stream
# speedup vs baseline: 1.0574x; 1.0237x over previous
; #define LAS __attribute__((address_space(3)))
; __device__ __forceinline__ unsigned xb_add(unsigned* p, unsigned v) { return __hip_atomic_fetch_add(p, v, __ATOMIC_RELAXED, __HIP_MEMORY_SCOPE_AGENT); }
; __device__ __forceinline__ unsigned xb_xcc_id() { return (unsigned)__builtin_amdgcn_s_getreg((3 << 11) | 20) & 0xFu; }
; __device__ __forceinline__ XcdBarrier xcd_barrier_post(unsigned* bar, volatile LAS unsigned* st, bool tid0) {
;     XcdBarrier b; b.tid0 = tid0; b.bar = bar; b.x = xb_xcc_id(); b.st = st;
;     if (b.tid0) (void)xb_add(&bar[XB_XCNT(b.x)], 1u);
;     return b;
; __global__ void __launch_bounds__(NTHR, 2) mega(Params p, int lo, int hi) {
;     extern __shared__ __attribute__((aligned(16))) unsigned char lds_raw[];
;     LAS unsigned char* lds = (LAS unsigned char*)lds_raw;
;     volatile LAS unsigned* bst = (volatile LAS unsigned*)(lds + LDS_BYTES - 16);
;     const int wave0 = __builtin_amdgcn_readfirstlane((int)threadIdx.x >> 6);
;     if (threadIdx.x < 4) bst[threadIdx.x] = 0u;
;     __syncthreads();
;     (void)xcd_barrier_post((unsigned*)(p.ws + WS_CTL), bst, threadIdx.x == 0);
_ZN12_GLOBAL__N_14megaENS_6ParamsEii:
	s_load_dwordx4 s[64:67], s[0:1], 0x120
	s_load_dwordx8 s[4:11], s[0:1], 0x100
	s_mov_b32 s92, s2
	s_mov_b32 s100, 0
	v_cmp_gt_u32_e32 vcc, 4, v0
	s_waitcnt lgkmcnt(0)
	v_writelane_b32 v252, s4, 0
	s_nop 1
	v_writelane_b32 v252, s5, 1
	v_writelane_b32 v252, s6, 2
	v_writelane_b32 v252, s7, 3
	v_writelane_b32 v252, s8, 4
	v_writelane_b32 v252, s9, 5
	v_writelane_b32 v252, s10, 6
	v_writelane_b32 v252, s11, 7
	v_readfirstlane_b32 s6, v0
	s_and_saveexec_b64 s[2:3], vcc
	v_lshl_add_u32 v1, v0, 2, 0
	v_add_u32_e32 v1, 0x23ff0, v1
	v_mov_b32_e32 v2, 0
	ds_write_b32 v1, v2
	s_or_b64 exec, exec, s[2:3]
	s_waitcnt lgkmcnt(0)
	s_barrier
	v_cmp_eq_u32_e32 vcc, 0, v0
	s_getreg_b32 s7, hwreg(HW_REG_XCC_ID, 0, 4)
	s_and_saveexec_b64 s[2:3], vcc
	s_cbranch_execz .LBB0_5
	s_mov_b64 s[4:5], exec
	v_mbcnt_lo_u32_b32 v0, s4, 0
	v_mbcnt_hi_u32_b32 v0, s5, v0
	v_cmp_eq_u32_e32 vcc, 0, v0
	s_and_b64 s[8:9], exec, vcc
	s_mov_b64 exec, s[8:9]
	s_cbranch_execz .LBB0_5
	s_lshl_b32 s7, s7, 8
	s_and_b32 s7, s7, 0xf00
	s_bcnt1_i32_b64 s4, s[4:5]
	v_mov_b32_e32 v0, s7
	v_mov_b32_e32 v1, s4
	global_atomic_add v0, v1, s[66:67] offset:1024

; __global__ void __launch_bounds__(NTHR, 2) mega(Params p, int lo, int hi) {
;     ...
;     for (int ph = lo; ph < hi; ++ph) {
;         int lid_; asm volatile("v_mbcnt_lo_u32_b32 %0, -1, 0\n\tv_mbcnt_hi_u32_b32 %0, -1, %0" : "=v"(lid_));
;         int tid = wave0 * 64 + lid_; asm volatile("" : "+v"(tid));
;         const int lane = tid & 63, wave = __builtin_amdgcn_readfirstlane(tid >> 6);
;         unsigned char* ws = p.ws;
;         const Ph P = phase_at(ph);
;         const int li = P.layer, jl = li >> 1;
;         const bf16* gA = nullptr; const bf16* gB = nullptr; int gN = 0, gK = 0; EpiAnyT<0> E{}; E.jl = jl; E.ws = ws; E.slot = -1; E.amul = 1.f; E.li = li; E.ldsb = lds; bool is_gemm = false;
;         switch (P.op) {
.Lsub_reenter:
	s_mov_b64 s[0:1], 0
	s_waitcnt lgkmcnt(0)
	s_barrier

; #define LAS __attribute__((address_space(3)))
; __device__ __forceinline__ void ph_ret_fast(const Params& p, int jl, LAS unsigned char* lds, int tid, int lane, int wave) {
;     const bf16* QK = (const bf16*)(p.ws + WS_QK); const bf16* V = (const bf16*)(p.ws + WS_V); bf16* O = (bf16*)(p.ws + WS_O);
;     const int fr = lane & 15, fq = lane >> 4, li_q = (lane & 15) >> 2, li_p = lane & 3;
;     for (int u = blockIdx.x; u < BATCH * RH * 8; u += gridDim.x) {
;         const int es = u & 7, h = (u >> 3) & 3, b = u >> 5;
;         const float gamma = 1.0f - exp2f(-5.0f - (float)h), lg = log2f(gamma), g128 = exp2f(128.f * lg), g127 = exp2f(127.f * lg);
;         const int it_ = wave < 4 ? wave : 11 - wave, i0 = 16 * it_, d0 = 32 * wave;
.LBB0_339:
	s_andn2_b64 vcc, exec, s[0:1]
	s_cbranch_vccnz .LBB0_464
	v_writelane_b32 v255, s46, 23
	v_writelane_b32 v255, s44, 16
	v_readlane_b32 s0, v252, 38
	v_readlane_b32 s1, v252, 39
	v_writelane_b32 v255, s45, 17
	v_writelane_b32 v255, s69, 25
	v_writelane_b32 v255, s68, 26
	v_writelane_b32 v255, s56, 18
	s_andn2_b64 vcc, exec, s[0:1]
	s_nop 0
	v_writelane_b32 v255, s57, 19
	s_cmp_eq_u32 s100, 0
	s_cselect_b32 s100, 1, s100
	v_readlane_b32 s101, v254, 37
	s_lshr_b32 s101, s101, 7
	s_xor_b32 s101, s101, s100
	s_bitcmp0_b32 s101, 0
	s_cbranch_scc1 .LBB0_457
	s_cbranch_vccnz .LBB0_457
	v_readlane_b32 s2, v255, 15
	s_sub_i32 s0, 11, s2
	s_cmp_lt_i32 s2, 4
	s_cselect_b32 s0, s2, s0
	s_lshl_b32 s13, s0, 4
	s_movk_i32 s1, 0x840
	v_cmp_gt_i32_e64 s[4:5], s1, v194
	s_add_i32 s15, s13, 0xffffff90
	s_cmp_gt_i32 s0, 6
	v_writelane_b32 v255, s4, 27
	v_lshlrev_b32_e32 v8, 4, v194
	v_and_b32_e32 v3, 3, v194
	v_writelane_b32 v255, s5, 28
	s_cselect_b64 s[4:5], -1, 0
	s_waitcnt lgkmcnt(0)
	v_and_b32_e32 v2, 0x1f0, v8
	v_bfe_u32 v5, v194, 2, 2
	v_lshrrev_b32_e32 v4, 4, v238
	v_writelane_b32 v255, s4, 29
	v_add_u32_e32 v9, 0, v2
	v_and_b32_e32 v2, 0x70, v8
	v_readlane_b32 s1, v253, 63
	v_lshlrev_b32_e32 v14, 3, v3
	v_writelane_b32 v255, s5, 30
	v_add_u32_e32 v10, s1, v2
	v_lshlrev_b32_e32 v12, 2, v4
	v_add_u32_e32 v165, s1, v14
	v_lshl_or_b32 v15, v4, 3, v5
	v_mov_b32_e32 v4, s1
	s_movk_i32 s1, 0x90
	v_and_b32_e32 v0, 15, v194
	v_mad_u32_u24 v17, v15, s1, v4
	v_lshl_or_b32 v4, s2, 5, v12
	v_readlane_b32 s2, v255, 25
	v_or_b32_e32 v11, s13, v0
	s_lshl_b32 s2, s2, 3
	v_writelane_b32 v255, s2, 31
	v_cmp_lt_i32_e64 s[2:3], v11, v12
	s_waitcnt vmcnt(0)
	v_or_b32_e32 v28, 2, v12
	v_or_b32_e32 v29, 33, v12
	v_writelane_b32 v255, s2, 32
	s_waitcnt vmcnt(2)
	v_or_b32_e32 v30, 0x41, v12
	s_waitcnt lgkmcnt(0)
	v_cmp_lt_i32_e64 s[28:29], v11, v29
	v_writelane_b32 v255, s3, 33
	v_cmp_gt_i32_e64 s[2:3], v11, v12
	v_or_b32_e32 v29, 34, v12
	v_cmp_lt_i32_e64 s[46:47], v11, v30
	v_writelane_b32 v255, s2, 34
	v_or_b32_e32 v30, 0x42, v12
	v_or_b32_e32 v6, s13, v12
	v_writelane_b32 v255, s3, 35
	v_cmp_lt_i32_e64 s[2:3], v11, v28
	v_or_b32_e32 v28, 3, v12
	v_cmp_lt_i32_e64 s[16:17], v11, v28
	v_or_b32_e32 v28, 16, v12
	v_cmp_lt_i32_e64 s[30:31], v11, v29
	v_or_b32_e32 v29, 35, v12
	v_cmp_lt_i32_e64 s[48:49], v11, v30
	v_or_b32_e32 v30, 0x43, v12
	v_or_b32_e32 v7, 1, v6
	v_cmp_lt_i32_e64 s[18:19], v11, v28
	v_or_b32_e32 v28, 17, v12
	v_cmp_lt_i32_e64 s[34:35], v11, v29
	v_or_b32_e32 v29, 48, v12
	v_cmp_lt_i32_e64 s[50:51], v11, v30
	v_or_b32_e32 v30, 0x50, v12
	v_cmp_lt_i32_e64 s[20:21], v11, v28
	v_or_b32_e32 v28, 18, v12
	v_cmp_lt_i32_e64 s[36:37], v11, v29
	v_or_b32_e32 v29, 49, v12
	v_cmp_lt_i32_e64 s[52:53], v11, v30
	v_or_b32_e32 v30, 0x51, v12
	v_cvt_f32_i32_e32 v170, v7
	v_or_b32_e32 v7, 2, v6
	v_cmp_lt_i32_e64 s[22:23], v11, v28
	v_or_b32_e32 v28, 19, v12
	v_cmp_lt_i32_e64 s[38:39], v11, v29
	v_or_b32_e32 v29, 50, v12
	v_cmp_lt_i32_e64 s[54:55], v11, v30
	v_or_b32_e32 v30, 0x52, v12
	v_cvt_f32_i32_e32 v171, v7
	v_or_b32_e32 v7, 3, v6
	v_add_u32_e32 v6, 4, v6
	v_cmp_lt_i32_e64 s[24:25], v11, v28
	v_or_b32_e32 v28, 32, v12
	v_cmp_lt_i32_e64 s[40:41], v11, v29
	v_or_b32_e32 v29, 51, v12
	v_cmp_lt_i32_e64 s[56:57], v11, v30
	v_or_b32_e32 v30, 0x53, v12
	v_cvt_f32_i32_e32 v173, v6
	v_or_b32_e32 v6, v12, v5
	v_cmp_lt_i32_e64 s[42:43], v11, v29
	v_or_b32_e32 v29, 64, v12
	v_cmp_lt_i32_e64 s[58:59], v11, v30
	v_or_b32_e32 v30, 0x60, v12
	v_mul_u32_u24_e32 v174, 0x90, v6
	v_or_b32_e32 v6, v28, v5
	v_mul_u32_u24_e32 v175, 0x90, v6
	v_or_b32_e32 v6, v29, v5
	v_or_b32_e32 v5, v30, v5
	v_mul_u32_u24_e32 v177, 0x90, v5
	v_or_b32_e32 v5, 32, v15
	v_mul_u32_u24_e32 v176, 0x90, v6
	v_mul_u32_u24_e32 v6, 0x210, v5
	v_add3_u32 v178, 0, v6, v14
	v_or_b32_e32 v6, 48, v238
	v_mul_u32_u24_e32 v180, 0x210, v6
	v_or_b32_e32 v6, 1, v4
	s_waitcnt vmcnt(1)
	v_add_u32_e32 v19, 0x200, v194
	v_cvt_f32_i32_e32 v172, v7
	v_ashrrev_i32_e32 v7, 31, v6
	v_ashrrev_i32_e32 v20, 5, v19
	v_ashrrev_i32_e32 v27, 3, v194
	v_ashrrev_i32_e32 v19, 3, v19
	s_cmp_gt_i32 s0, -1
	v_lshlrev_b64 v[100:101], 11, v[6:7]
	v_or_b32_e32 v6, 2, v4
	v_add_u32_e32 v21, 0x400, v194
	s_waitcnt vmcnt(0)
; __device__ __forceinline__ void ph_ret_fast(const Params& p, int jl, LAS unsigned char* lds, int tid, int lane, int wave) {
;     ...
;     for (int u = blockIdx.x; u < BATCH * RH * 8; u += gridDim.x) {
;         const int es = u & 7, h = (u >> 3) & 3, b = u >> 5;
;         const float gamma = 1.0f - exp2f(-5.0f - (float)h), lg = log2f(gamma), g128 = exp2f(128.f * lg), g127 = exp2f(127.f * lg);
;         const int it_ = wave < 4 ? wave : 11 - wave, i0 = 16 * it_, d0 = 32 * wave;
	v_add_u32_e32 v22, 0x600, v194
	v_add_u32_e32 v23, 0x800, v194
	v_add_u32_e32 v24, 0xa00, v194
	v_add_u32_e32 v25, 0xc00, v194
	v_add_u32_e32 v26, 0xe00, v194
	v_cvt_f32_i32_e32 v166, v27
	v_mul_lo_u32 v27, v27, s1
	v_cvt_f32_i32_e32 v167, v19
	v_mul_lo_u32 v19, v19, s1
	s_cselect_b64 s[4:5], -1, 0
	v_writelane_b32 v255, s2, 36
	s_cmp_gt_i32 s0, 1
	v_readlane_b32 s1, v254, 0
	v_ashrrev_i32_e32 v7, 31, v6
	v_ashrrev_i32_e32 v18, 5, v194
	s_movk_i32 s12, 0x210
	v_ashrrev_i32_e32 v21, 5, v21
	v_ashrrev_i32_e32 v22, 5, v22
	v_ashrrev_i32_e32 v23, 5, v23
	v_ashrrev_i32_e32 v24, 5, v24
	v_ashrrev_i32_e32 v25, 5, v25
	v_ashrrev_i32_e32 v26, 5, v26
	v_writelane_b32 v255, s3, 37
	s_cselect_b64 s[2:3], -1, 0
	s_cmp_gt_i32 s0, 3
	v_mov_b32_e32 v32, s1
	v_mov_b32_e32 v33, 0x4200
	v_lshlrev_b64 v[102:103], 11, v[6:7]
	v_or_b32_e32 v6, 3, v4
	v_mul_lo_u32 v18, v18, s12
	v_mul_lo_u32 v20, v20, s12
	v_mul_lo_u32 v21, v21, s12
	v_mul_lo_u32 v22, v22, s12
	v_mul_lo_u32 v23, v23, s12
	v_mul_lo_u32 v24, v24, s12
	v_mul_lo_u32 v25, v25, s12
	v_mul_lo_u32 v26, v26, s12
	s_cselect_b64 s[92:93], -1, 0
	s_cmp_gt_i32 s0, 5
	v_or_b32_e32 v31, 0x61, v12
	v_mad_u32_u24 v32, v0, s12, v32
	v_mad_u32_u24 v33, v0, s12, v33
	v_readlane_b32 s12, v255, 13
	v_ashrrev_i32_e32 v7, 31, v6
	s_cselect_b64 s[84:85], -1, 0
	v_cmp_lt_i32_e64 s[62:63], v11, v31
	v_or_b32_e32 v31, 0x62, v12
	s_and_b32 s27, s12, 0xffffffc0
	v_lshlrev_b64 v[104:105], 11, v[6:7]
	v_or_b32_e32 v6, 16, v4
	v_cmp_lt_i32_e64 s[64:65], v11, v31
	v_or_b32_e32 v31, 0x63, v12
	v_ashrrev_i32_e32 v7, 31, v6
	s_cmpk_gt_i32 s0, 0xff86
	v_mul_u32_u24_e32 v16, 0x210, v15
	v_cmp_lt_i32_e64 s[66:67], v11, v31
	v_or_b32_e32 v31, 0x70, v12
	v_mul_u32_u24_e32 v15, 0x90, v5
	v_lshlrev_b32_e32 v5, 1, v4
	v_readlane_b32 s12, v254, 1
	v_lshlrev_b64 v[106:107], 11, v[6:7]
	v_or_b32_e32 v6, 17, v4
	s_cselect_b64 s[74:75], -1, 0
	v_cvt_f32_i32_e32 v164, v11
	v_cmp_lt_i32_e64 s[68:69], v11, v31
	v_or_b32_e32 v31, 0x71, v12
	v_add_u32_e32 v179, s1, v5
	v_add_u32_e32 v181, s12, v5
	v_ashrrev_i32_e32 v5, 31, v4
	v_ashrrev_i32_e32 v7, 31, v6
	v_writelane_b32 v255, s74, 21
	v_and_b32_e32 v13, 48, v194
	v_and_b32_e32 v2, 1, v194
	v_cmp_lt_i32_e64 s[70:71], v11, v31
	v_or_b32_e32 v31, 0x72, v12
	v_lshlrev_b64 v[98:99], 11, v[4:5]
	v_lshlrev_b64 v[108:109], 11, v[6:7]
	v_or_b32_e32 v6, 18, v4
	v_or_b32_e32 v4, 19, v4
	v_writelane_b32 v255, s75, 22
	s_add_i32 s0, s13, 0x790
	v_cmp_eq_u32_e64 s[6:7], 0, v2
	v_and_b32_e32 v2, 12, v194
	v_mul_u32_u24_e32 v168, 0x210, v0
	v_cmp_lt_i32_e64 s[10:11], v11, v28
	v_cmp_lt_i32_e64 s[44:45], v11, v29
	v_cmp_lt_i32_e64 s[72:73], v11, v31
	v_or_b32_e32 v31, 0x73, v12
	v_add_u32_e32 v34, s1, v33
	v_add_u32_e32 v35, s1, v13
	v_add3_u32 v16, 0, v16, v14
	v_add_u32_e32 v28, 0x4200, v178
	v_add_u32_e32 v29, 0x8400, v178
	v_ashrrev_i32_e32 v7, 31, v6
	v_ashrrev_i32_e32 v5, 31, v4
	v_or_b32_e32 v182, v12, v3
	v_writelane_b32 v255, s0, 38
	v_readlane_b32 s0, v254, 37
	v_cmp_gt_u32_e64 s[8:9], 2, v3
	v_add3_u32 v169, 0, v168, v13
	v_cmp_lt_i32_e64 s[60:61], v11, v30
	v_lshlrev_b64 v[110:111], 11, v[6:7]
	v_lshlrev_b64 v[112:113], 11, v[4:5]
	s_mov_b32 s14, s13
	v_add_u32_e32 v183, 0xfffffe00, v194
	v_add_u32_e32 v184, s1, v8
	v_writelane_b32 v255, s15, 40
	v_or_b32_e32 v185, s15, v182
	v_lshlrev_b32_e32 v114, 1, v2
	v_lshlrev_b32_e32 v116, 2, v0
	v_add_u32_e32 v186, v9, v18
	v_add_u32_e32 v187, v9, v20
	v_add_u32_e32 v188, v9, v21
	v_add_u32_e32 v189, v9, v22
	v_add_u32_e32 v190, v9, v23
	v_add_u32_e32 v191, v9, v24
	v_add_u32_e32 v192, v9, v25
	v_add_u32_e32 v193, v9, v26
	v_add_u32_e32 v195, v10, v27
	v_add_u32_e32 v196, v10, v19
	v_add_u32_e32 v197, v32, v13
	v_add_u32_e32 v198, v35, v33
	v_add_u32_e32 v199, v34, v13
	v_add_u32_e32 v200, s27, v16
	v_add_u32_e32 v201, v17, v14
	v_add_u32_e32 v202, v165, v15
	v_add_u32_e32 v203, s27, v28
	s_mov_b32 s15, s27
	v_add_u32_e32 v204, s27, v29
	s_and_b32 s101, s0, 7
	s_lshl_b32 s101, s101, 5
	s_lshr_b32 s13, s0, 3
	s_or_b32 s13, s13, s101
	v_cmp_lt_i32_e64 s[74:75], v11, v31
	s_branch .LBB0_343

; #define LAS __attribute__((address_space(3)))
; __device__ __forceinline__ float bf_lo(unsigned w) { return __uint_as_float(w << 16); }
; __device__ __forceinline__ float bf_hi(unsigned w) { return __uint_as_float(w & 0xffff0000u); }
; __device__ __forceinline__ void ph_ret_fast(const Params& p, int jl, LAS unsigned char* lds, int tid, int lane, int wave) {
;     ...
;     {
;         LAS float* sq = (LAS float*)lds; LAS float* sk = sq + 256; LAS float* red = sk + 256;
;         const int e4 = tid & 127, dq = tid >> 7;
;         for (int it = blockIdx.x; it < SB * RH; it += gridDim.x) {
;             const int h = it & 3, s = it >> 2, row = MP + s;
;             const float gamma = 1.0f - exp2f(-5.0f - (float)h);
;             __syncthreads();
;             if (tid < 256) sq[tid] = bf_lo((unsigned)QK[(size_t)row * 2048 + 256 * h + tid]);
;             else sk[tid - 256] = bf_lo((unsigned)QK[(size_t)row * 2048 + 1024 + 256 * h + (tid - 256)]);
;             const v2u vv = *(const v2u*)(V + (size_t)row * 2048 + 512 * h + 4 * e4);
;             const f32x4 v4 = (f32x4){bf_lo(vv.x), bf_hi(vv.x), bf_lo(vv.y), bf_hi(vv.y)};
;             __syncthreads();
;             const float* sin_ = p.in[I_SRET] + ((((size_t)jl * SB + s) * RH + h) * RDK) * RDV + 4 * e4;
;             float* sout = p.out + O_RETS + ((((size_t)jl * SB + s) * RH + h) * RDK) * RDV + 4 * e4;
.LBB0_457:
	v_readlane_b32 s0, v252, 60
	v_readlane_b32 s1, v252, 61
	v_readlane_b32 s64, v254, 38
	v_readlane_b32 s56, v255, 18
	v_readlane_b32 s90, v254, 43
	v_readlane_b32 s62, v254, 47
	v_readlane_b32 s36, v254, 49
	v_readlane_b32 s44, v255, 16
	s_andn2_b64 vcc, exec, s[0:1]
	v_readlane_b32 s92, v254, 37
	v_readlane_b32 s65, v254, 39
	v_readlane_b32 s66, v254, 40
	v_readlane_b32 s67, v254, 41
	v_readlane_b32 s57, v255, 19
	v_readlane_b32 s39, v254, 42
	v_readlane_b32 s91, v254, 44
	v_readlane_b32 s63, v254, 48
	v_readlane_b32 s37, v254, 50
	v_readlane_b32 s93, v254, 53
	s_movk_i32 s24, 0x2000
	s_movk_i32 s25, 0x4000
	s_mov_b32 s27, 0x8000
	s_waitcnt lgkmcnt(0)
	s_mov_b32 s28, 0xa000
	s_mov_b32 s29, 0x46f9d000
	v_readlane_b32 s34, v255, 15
	v_readlane_b32 s68, v255, 26
	v_readlane_b32 s69, v255, 25
	v_readlane_b32 s45, v255, 17
	s_mov_b64 s[72:73], 0
	v_readlane_b32 s46, v255, 23
	v_readlane_b32 s101, v254, 37
	s_lshr_b32 s101, s101, 7
	s_xor_b32 s101, s101, s100
	s_bitcmp1_b32 s101, 0
	s_cbranch_scc1 .LBB0_464
	s_cbranch_vccnz .LBB0_464
	s_movk_i32 s0, 0x100
	v_cmp_gt_i32_e64 s[4:5], s0, v194
	s_movk_i32 s0, 0x80
	v_ashrrev_i32_e32 v2, 7, v194
	v_cmp_gt_u32_e64 s[6:7], s0, v194
	v_readlane_b32 s0, v255, 12
	s_lshl_b32 s0, s0, 27
	v_ashrrev_i32_e32 v3, 31, v2
	v_lshlrev_b32_e32 v0, 2, v194
	s_and_b32 s94, s0, 0x10000000
	v_lshlrev_b64 v[4:5], 11, v[2:3]
	s_waitcnt vmcnt(0)
	v_add_u32_e32 v30, 0, v0
	v_and_b32_e32 v0, 0x1fc, v0
	v_lshl_add_u64 v[4:5], s[94:95], 0, v[4:5]
	v_and_b32_e32 v3, 0x7f, v194
	v_readlane_b32 s8, v253, 20
	v_lshl_add_u32 v31, v0, 2, 0
	v_lshl_or_b32 v4, v3, 4, v4
	v_readlane_b32 s12, v253, 24
	v_readlane_b32 s13, v253, 25
	v_mov_b32_e32 v195, v1
	v_ashrrev_i32_e32 v7, 31, v194
	v_mov_b32_e32 v6, v194
	v_lshl_add_u32 v32, v2, 11, v31
	v_lshl_add_u64 v[8:9], s[64:65], 0, v[4:5]
	v_lshl_add_u64 v[10:11], s[12:13], 0, v[4:5]
	v_lshl_add_u32 v33, v2, 2, 0
	s_mov_b32 s8, s92
	v_readlane_b32 s9, v253, 21
	v_readlane_b32 s10, v253, 22
	v_readlane_b32 s11, v253, 23
	v_readlane_b32 s14, v253, 26
	v_readlane_b32 s15, v253, 27
	v_readlane_b32 s16, v253, 28
	v_readlane_b32 s17, v253, 29
	v_readlane_b32 s18, v253, 30
	v_readlane_b32 s19, v253, 31
	v_readlane_b32 s20, v253, 32
	v_readlane_b32 s21, v253, 33
	v_readlane_b32 s22, v253, 34
	v_readlane_b32 s23, v253, 35
	s_branch .LBB0_460

; template <class Epi, class Sched, bool ALIGN_EPI = false, bool SP2 = false>
; __device__ __forceinline__ void gemm_phase(PG8_LAS unsigned char* lds, const Gemm g, const Sched& S, const Epi& E, int tid_in) {
;     ...
; #pragma unroll
;         for (int a = 0; a < 2; ++a)
; #pragma unroll
;             for (int b = 0; b < 2; ++b)
; #pragma unroll
;                 for (int m = 0; m < 4; ++m)
; #pragma unroll
;                     for (int n = 0; n < 2; ++n) acc[a][b][m][n] = (f32x4){0.f, 0.f, 0.f, 0.f};
;         cur = nxt; cA = nA; cB = nB; ++ui; ntc = PG8_KNT(cur.pn);
.LBB0_846:
	v_mov_b32_e32 v125, 0
	v_mov_b32_e32 v124, v125
	v_mov_b32_e32 v123, v125
	v_mov_b32_e32 v122, v125
	v_mov_b32_e32 v117, v125
	v_mov_b32_e32 v116, v125
	v_mov_b32_e32 v115, v125
	v_mov_b32_e32 v114, v125
	v_mov_b32_e32 v109, v125
	v_mov_b32_e32 v108, v125
	v_mov_b32_e32 v107, v125
	v_mov_b32_e32 v106, v125
	v_mov_b32_e32 v101, v125
	v_mov_b32_e32 v100, v125
	v_mov_b32_e32 v99, v125
	v_mov_b32_e32 v98, v125
	v_mov_b32_e32 v93, v125
	v_mov_b32_e32 v92, v125
	v_mov_b32_e32 v91, v125
	v_mov_b32_e32 v90, v125
	v_mov_b32_e32 v85, v125
	v_mov_b32_e32 v84, v125
	v_mov_b32_e32 v83, v125
	v_mov_b32_e32 v82, v125
	v_mov_b32_e32 v77, v125
	v_mov_b32_e32 v76, v125
	v_mov_b32_e32 v75, v125
	v_mov_b32_e32 v74, v125
	v_mov_b32_e32 v69, v125
	v_mov_b32_e32 v68, v125
	v_mov_b32_e32 v67, v125
	v_mov_b32_e32 v66, v125
	v_mov_b32_e32 v129, v125
	v_mov_b32_e32 v128, v125
	v_mov_b32_e32 v127, v125
	v_mov_b32_e32 v126, v125
	v_mov_b32_e32 v121, v125
	v_mov_b32_e32 v120, v125
	v_mov_b32_e32 v119, v125
	v_mov_b32_e32 v118, v125
	v_mov_b32_e32 v113, v125
	v_mov_b32_e32 v112, v125
	v_mov_b32_e32 v111, v125
	v_mov_b32_e32 v110, v125
	v_mov_b32_e32 v105, v125
	v_mov_b32_e32 v104, v125
	v_mov_b32_e32 v103, v125
	v_mov_b32_e32 v102, v125
	v_mov_b32_e32 v97, v125
	v_mov_b32_e32 v96, v125
	v_mov_b32_e32 v95, v125
	v_mov_b32_e32 v94, v125
	v_mov_b32_e32 v89, v125
	v_mov_b32_e32 v88, v125
	v_mov_b32_e32 v87, v125
	v_mov_b32_e32 v86, v125
	v_mov_b32_e32 v81, v125
	v_mov_b32_e32 v80, v125
	v_mov_b32_e32 v79, v125
	v_mov_b32_e32 v78, v125
	v_mov_b32_e32 v73, v125
	v_mov_b32_e32 v72, v125
	v_mov_b32_e32 v71, v125
	v_mov_b32_e32 v70, v125
	v_mov_b32_e32 v61, v125
	v_mov_b32_e32 v60, v125
	v_mov_b32_e32 v59, v125
	v_mov_b32_e32 v58, v125
	v_mov_b32_e32 v53, v125
	v_mov_b32_e32 v52, v125
	v_mov_b32_e32 v51, v125
	v_mov_b32_e32 v50, v125
	v_mov_b32_e32 v45, v125
	v_mov_b32_e32 v44, v125
	v_mov_b32_e32 v43, v125
	v_mov_b32_e32 v42, v125
	v_mov_b32_e32 v37, v125
	v_mov_b32_e32 v36, v125
	v_mov_b32_e32 v35, v125
	v_mov_b32_e32 v34, v125
	v_mov_b32_e32 v29, v125
	v_mov_b32_e32 v28, v125
	v_mov_b32_e32 v27, v125
	v_mov_b32_e32 v26, v125
	v_mov_b32_e32 v21, v125
	v_mov_b32_e32 v20, v125
	v_mov_b32_e32 v19, v125
	v_mov_b32_e32 v18, v125
	v_mov_b32_e32 v13, v125
	v_mov_b32_e32 v12, v125
	v_mov_b32_e32 v11, v125
	v_mov_b32_e32 v10, v125
	v_mov_b32_e32 v9, v125
	v_mov_b32_e32 v8, v125
	v_mov_b32_e32 v7, v125
	v_mov_b32_e32 v6, v125
	v_mov_b32_e32 v65, v125
	v_mov_b32_e32 v64, v125
	v_mov_b32_e32 v63, v125
	v_mov_b32_e32 v62, v125
	v_mov_b32_e32 v57, v125
	v_mov_b32_e32 v56, v125
	v_mov_b32_e32 v55, v125
	v_mov_b32_e32 v54, v125
	v_mov_b32_e32 v49, v125
	v_mov_b32_e32 v48, v125
	v_mov_b32_e32 v47, v125
	v_mov_b32_e32 v46, v125
	v_mov_b32_e32 v41, v125
	v_mov_b32_e32 v40, v125
	v_mov_b32_e32 v39, v125
	v_mov_b32_e32 v38, v125
	v_mov_b32_e32 v33, v125
	v_mov_b32_e32 v32, v125
	v_mov_b32_e32 v31, v125
	v_mov_b32_e32 v30, v125
	s_waitcnt vmcnt(0)
	v_mov_b32_e32 v25, v125
	v_mov_b32_e32 v24, v125
	v_mov_b32_e32 v23, v125
	v_mov_b32_e32 v22, v125
	v_mov_b32_e32 v17, v125
	v_mov_b32_e32 v16, v125
	v_mov_b32_e32 v15, v125
	v_mov_b32_e32 v14, v125
	v_mov_b32_e32 v5, v125
	v_mov_b32_e32 v4, v125
	v_mov_b32_e32 v3, v125
	v_mov_b32_e32 v2, v125
	s_and_b64 vcc, exec, s[34:35]
	s_cbranch_vccnz .LBB0_608
	s_branch .LBB0_609
.Lsub_tramp1:
	s_branch .Lsub_reenter
.LBB0_847:
	s_andn2_b64 vcc, exec, s[0:1]
	s_cbranch_vccz .LBB0_1127
	s_branch .LBB0_1147

; #define LAS __attribute__((address_space(3)))
; __device__ __forceinline__ unsigned xb_xcc_id() { return (unsigned)__builtin_amdgcn_s_getreg((3 << 11) | 20) & 0xFu; }
; __global__ void __launch_bounds__(NTHR, 2) mega(Params p, int lo, int hi) {
;     ...
;     for (int ph = lo; ph < hi; ++ph) {
;         int lid_; asm volatile("v_mbcnt_lo_u32_b32 %0, -1, 0\n\tv_mbcnt_hi_u32_b32 %0, -1, %0" : "=v"(lid_));
;         int tid = wave0 * 64 + lid_; asm volatile("" : "+v"(tid));
;         const int lane = tid & 63, wave = __builtin_amdgcn_readfirstlane(tid >> 6);
;         unsigned char* ws = p.ws;
;         const Ph P = phase_at(ph);
;     ...
;         if (ph + 1 < hi) { XcdBarrier bar; bar.tid0 = tid == 0; bar.bar = (unsigned*)(p.ws + WS_CTL); bar.x = xb_xcc_id(); bar.st = (volatile LAS unsigned*)(lds + LDS_BYTES - 16); xcd_barrier(bar); }
;     }
.LBB0_1548:
	s_cmp_eq_u32 s100, 1
	s_cbranch_scc0 .Lsub_not1
	s_mov_b32 s100, 2
	s_branch .Lsub_tramp1
.Lsub_not1:
	s_mov_b32 s100, 0
	s_add_i32 s56, s56, 1
	s_cmp_ge_i32 s56, s57
	s_mov_b64 s[0:1], -1
	s_cbranch_scc0 .LBB0_1549
	s_getpc_b64 s[98:99]
